# attention inner loop: exp results in adjacent register pairs, row sums accumulated with 8 v_pk_add_f32 per KV half into two f32 partial sums (folded into the row sum once per unit) instead of 16 depen
# speedup vs baseline: 1.0036x; 1.0002x over previous
; #define LAS __attribute__((address_space(3)))
; __device__ __forceinline__ void attn_unit(const Params& p, LAS unsigned char* lds, int bh, int qb, float mshift, int tid, int lane, int wave) {
;     ...
;     f32x16 o[2]; float lsum = 0.f;
; #pragma unroll
;     for (int i = 0; i < 16; ++i) { o[0][i] = 0.f; o[1][i] = 0.f; }
;     const int NT = 4 * (qb + 1);
;     const int srow = tid >> 3, sch = tid & 7;
;     const bf16_t* kp = Kg + ((size_t)(b * S_ + srow)) * 512 + h * 64 + 8 * sch;
;     const bf16_t* vp = Vg + ((size_t)(bh * 64 + srow)) * S_ + 8 * sch;
;     u32x4 kreg = *(const u32x4*)kp, vreg = *(const u32x4*)vp, areg = (u32x4){0u, 0u, 0u, 0u};
;     if (tid < 64) areg = kaug[tid];
;     { LAS unsigned char* bb = lds; *(LAS u32x4*)(bb + AB_K + srow * 144 + sch * 16) = kreg; *(LAS u32x4*)(bb + AB_V + srow * 144 + sch * 16) = vreg; if (tid < 64) *(LAS u32x4*)(bb + AB_A + tid * 16) = areg; }
;     __syncthreads();
.Lat_join:
	v_mov_b32_e32 v250, 0
	v_mov_b32_e32 v251, 0
	ds_write_b128 v101, v[20:23]
	ds_write_b128 v101, v[24:27] offset:9216
	s_and_saveexec_b64 s[36:37], s[8:9]
	v_add_u32_e32 v20, 0, v102
	ds_write_b128 v20, v[88:91] offset:18432
	s_or_b64 exec, exec, s[36:37]
	s_lshl_b32 s48, s38, 2
	v_mov_b32_e32 v64, 0
	s_xor_b64 s[36:37], s[10:11], -1
	v_cndmask_b32_e64 v87, 0, v19, s[6:7]
	v_cndmask_b32_e64 v86, 0, v18, s[6:7]
	v_cndmask_b32_e64 v85, 0, v17, s[6:7]
	v_cndmask_b32_e64 v84, 0, v16, s[6:7]
	s_mov_b32 s47, 0
	s_sub_i32 s49, 0, s16
	s_sub_i32 s50, 0, s48
	v_mov_b64_e32 v[66:67], v[168:169]
	v_mov_b64_e32 v[170:171], v[166:167]
	v_mov_b64_e32 v[172:173], v[164:165]
	v_mov_b32_e32 v16, 0
	v_mov_b32_e32 v17, v64
	v_mov_b32_e32 v18, v64
	v_mov_b32_e32 v19, v64
	v_mov_b32_e32 v20, v64
	v_mov_b32_e32 v21, v64
	v_mov_b32_e32 v22, v64
	v_mov_b32_e32 v23, v64
	v_mov_b32_e32 v24, v64
	v_mov_b32_e32 v25, v64
	v_mov_b32_e32 v26, v64
	v_mov_b32_e32 v27, v64
	v_mov_b32_e32 v28, v64
	v_mov_b32_e32 v29, v64
	v_mov_b32_e32 v30, v64
	v_mov_b32_e32 v31, v64
	v_mov_b32_e32 v32, v64
	v_mov_b32_e32 v33, v64
	v_mov_b32_e32 v34, v64
	v_mov_b32_e32 v35, v64
	v_mov_b32_e32 v36, v64
	v_mov_b32_e32 v37, v64
	v_mov_b32_e32 v38, v64
	v_mov_b32_e32 v39, v64
	v_mov_b32_e32 v40, v64
	v_mov_b32_e32 v41, v64
	v_mov_b32_e32 v42, v64
	v_mov_b32_e32 v43, v64
	v_mov_b32_e32 v44, v64
	v_mov_b32_e32 v45, v64
	v_mov_b32_e32 v46, v64
	v_mov_b32_e32 v47, v64
	s_waitcnt lgkmcnt(0)
	s_barrier
	s_branch .LBB0_360

; #define LAS __attribute__((address_space(3)))
; __device__ __forceinline__ unsigned cvtpk_s(float lo, float hi) { f32x2_t v = {lo, hi}; bf16x2_t b = __builtin_convertvector(v, bf16x2_t); return __builtin_bit_cast(unsigned, b); }
; __device__ __forceinline__ void attn_unit(const Params& p, LAS unsigned char* lds, int bh, int qb, float mshift, int tid, int lane, int wave) {
;     ...
; #pragma unroll
;             for (int i = 0; i < 16; ++i) { C[i] = __builtin_amdgcn_exp2f(C[i]); lsum += C[i]; }
; #pragma unroll
;             for (int s = 0; s < 2; ++s) {
;                 u32x4 pw; pw.x = cvtpk_s(C[8 * s + 0], C[8 * s + 1]); pw.y = cvtpk_s(C[8 * s + 2], C[8 * s + 3]); pw.z = cvtpk_s(C[8 * s + 4], C[8 * s + 5]); pw.w = cvtpk_s(C[8 * s + 6], C[8 * s + 7]);
;                 const bf16x8 pa = __builtin_bit_cast(bf16x8, pw);
; #pragma unroll
;                 for (int dh = 0; dh < 2; ++dh) { const bf16x8 vf = *(const LAS bf16x8*)(bb + AB_V + (32 * dh + r32) * 144 + (32 * kh + 16 * s + 8 * hi) * 2);
;                     o[dh] = __builtin_amdgcn_mfma_f32_32x32x16_bf16(pa, vf, o[dh], 0, 0, 0); }
;             }
.LBB0_365:
	s_nop 10
	v_exp_f32_e32 v196, v48
	v_exp_f32_e32 v197, v49
	v_exp_f32_e32 v198, v50
	v_exp_f32_e32 v199, v51
	v_exp_f32_e32 v200, v52
	v_exp_f32_e32 v201, v53
	v_exp_f32_e32 v202, v54
	v_exp_f32_e32 v203, v55
	v_cvt_pk_bf16_f32 v48, v196, v197
	v_cvt_pk_bf16_f32 v49, v198, v199
	v_cvt_pk_bf16_f32 v50, v200, v201
	v_cvt_pk_bf16_f32 v51, v202, v203
	ds_read_b128 v[52:55], v119 offset:9216
	v_exp_f32_e32 v246, v60
	v_add_u32_e32 v60, v123, v180
	v_exp_f32_e32 v204, v56
	v_exp_f32_e32 v205, v57
	v_exp_f32_e32 v206, v58
	v_exp_f32_e32 v207, v59
	ds_read_b128 v[56:59], v119 offset:9248
	s_waitcnt lgkmcnt(1)
	v_mfma_f32_32x32x16_bf16 v[16:31], v[48:51], v[52:55], v[16:31]
	ds_read_b128 v[52:55], v60 offset:9216
	v_exp_f32_e32 v247, v61
	v_exp_f32_e32 v248, v62
	v_exp_f32_e32 v249, v63
	ds_read_b128 v[60:63], v60 offset:9248
	s_waitcnt lgkmcnt(1)
	v_mfma_f32_32x32x16_bf16 v[32:47], v[48:51], v[52:55], v[32:47]
	v_cvt_pk_bf16_f32 v48, v204, v205
	v_cvt_pk_bf16_f32 v49, v206, v207
	v_cvt_pk_bf16_f32 v50, v246, v247
	v_cvt_pk_bf16_f32 v51, v248, v249
	s_nop 1
	v_mfma_f32_32x32x16_bf16 v[16:31], v[48:51], v[56:59], v[16:31]
	s_waitcnt lgkmcnt(0)
	v_mfma_f32_32x32x16_bf16 v[32:47], v[48:51], v[60:63], v[32:47]
	v_pk_add_f32 v[250:251], v[250:251], v[196:197]
	v_pk_add_f32 v[250:251], v[250:251], v[198:199]
	v_pk_add_f32 v[250:251], v[250:251], v[200:201]
	v_pk_add_f32 v[250:251], v[250:251], v[202:203]
	v_pk_add_f32 v[250:251], v[250:251], v[204:205]
	v_pk_add_f32 v[250:251], v[250:251], v[206:207]
	v_pk_add_f32 v[250:251], v[250:251], v[246:247]
	v_pk_add_f32 v[250:251], v[250:251], v[248:249]

; #define LAS __attribute__((address_space(3)))
; __device__ __forceinline__ unsigned cvtpk_s(float lo, float hi) { f32x2_t v = {lo, hi}; bf16x2_t b = __builtin_convertvector(v, bf16x2_t); return __builtin_bit_cast(unsigned, b); }
; __device__ __forceinline__ void attn_unit(const Params& p, LAS unsigned char* lds, int bh, int qb, float mshift, int tid, int lane, int wave) {
;     ...
; #pragma unroll
;             for (int i = 0; i < 16; ++i) { C[i] = __builtin_amdgcn_exp2f(C[i]); lsum += C[i]; }
; #pragma unroll
;             for (int s = 0; s < 2; ++s) {
;                 u32x4 pw; pw.x = cvtpk_s(C[8 * s + 0], C[8 * s + 1]); pw.y = cvtpk_s(C[8 * s + 2], C[8 * s + 3]); pw.z = cvtpk_s(C[8 * s + 4], C[8 * s + 5]); pw.w = cvtpk_s(C[8 * s + 6], C[8 * s + 7]);
;                 const bf16x8 pa = __builtin_bit_cast(bf16x8, pw);
; #pragma unroll
;                 for (int dh = 0; dh < 2; ++dh) { const bf16x8 vf = *(const LAS bf16x8*)(bb + AB_V + (32 * dh + r32) * 144 + (32 * kh + 16 * s + 8 * hi) * 2);
;                     o[dh] = __builtin_amdgcn_mfma_f32_32x32x16_bf16(pa, vf, o[dh], 0, 0, 0); }
;             }
.LBB0_369:
	s_nop 10
	v_exp_f32_e32 v196, v48
	v_exp_f32_e32 v197, v49
	v_exp_f32_e32 v198, v50
	v_exp_f32_e32 v199, v51
	v_exp_f32_e32 v200, v52
	v_exp_f32_e32 v201, v53
	v_exp_f32_e32 v202, v54
	v_exp_f32_e32 v203, v55
	v_cvt_pk_bf16_f32 v48, v196, v197
	v_cvt_pk_bf16_f32 v49, v198, v199
	v_cvt_pk_bf16_f32 v50, v200, v201
	v_cvt_pk_bf16_f32 v51, v202, v203
	ds_read_b128 v[52:55], v119 offset:9280
	ds_read_b128 v[184:187], v119 offset:9312
	s_waitcnt lgkmcnt(1)
	v_mfma_f32_32x32x16_bf16 v[16:31], v[48:51], v[52:55], v[16:31]
	ds_read_b128 v[52:55], v123 offset:9280
	v_exp_f32_e32 v204, v56
	v_exp_f32_e32 v205, v57
	v_exp_f32_e32 v206, v58
	v_exp_f32_e32 v207, v59
	v_exp_f32_e32 v60, v60
	v_exp_f32_e32 v61, v61
	v_exp_f32_e32 v62, v62
	v_exp_f32_e32 v63, v63
	ds_read_b128 v[56:59], v123 offset:9312
	s_waitcnt lgkmcnt(1)
	v_mfma_f32_32x32x16_bf16 v[32:47], v[48:51], v[52:55], v[32:47]
	v_cvt_pk_bf16_f32 v48, v204, v205
	v_cvt_pk_bf16_f32 v49, v206, v207
	v_cvt_pk_bf16_f32 v50, v60, v61
	v_cvt_pk_bf16_f32 v51, v62, v63
	s_nop 1
	v_mfma_f32_32x32x16_bf16 v[16:31], v[48:51], v[184:187], v[16:31]
	s_waitcnt lgkmcnt(0)
	v_mfma_f32_32x32x16_bf16 v[32:47], v[48:51], v[56:59], v[32:47]
	v_pk_add_f32 v[250:251], v[250:251], v[196:197]
	v_pk_add_f32 v[250:251], v[250:251], v[198:199]
	v_pk_add_f32 v[250:251], v[250:251], v[200:201]
	v_pk_add_f32 v[250:251], v[250:251], v[202:203]
	v_pk_add_f32 v[250:251], v[250:251], v[204:205]
	v_pk_add_f32 v[250:251], v[250:251], v[206:207]
	v_pk_add_f32 v[250:251], v[250:251], v[60:61]
	v_pk_add_f32 v[250:251], v[250:251], v[62:63]

; #define LAS __attribute__((address_space(3)))
; __device__ __forceinline__ void attn_unit(const Params& p, LAS unsigned char* lds, int bh, int qb, float mshift, int tid, int lane, int wave) {
;     ...
;     lsum += __shfl_xor(lsum, 32);
;     LAS float* lw = (LAS float*)(lds + A_LW + wave * 128);
;     if (hi == 0) lw[r32] = lsum;
.LBB0_380:
	v_add_f32_e32 v64, v250, v64
	v_add_f32_e32 v64, v251, v64
	v_and_b32_e32 v49, 64, v105
	v_xor_b32_e32 v48, 32, v105
	v_add_u32_e32 v49, 64, v49
	v_cmp_lt_i32_e32 vcc, v48, v49
	s_barrier
	s_nop 0
	v_cndmask_b32_e32 v48, v105, v48, vcc
	v_lshlrev_b32_e32 v48, 2, v48
	ds_bpermute_b32 v48, v48, v64
	s_waitcnt lgkmcnt(0)
	s_and_saveexec_b64 s[10:11], s[6:7]
	s_cbranch_execz .LBB0_353
	v_add_f32_e32 v48, v64, v48
	ds_write_b32 v182, v48 offset:38912
	s_branch .LBB0_353
